# re-sync wave groups at tile boundary so both halves run swiglu epilogue concurrently (dense+moe wi GEMMs)
# speedup vs baseline: 1.0142x; 1.0142x over previous
; template <class Epi, class Sched>
; __device__ __forceinline__ void gemm_phase(LAS unsigned char* lds, const int K, const int lda, const int ldb, const Sched& S, const Epi& E) {
;     ...
;         if (!has_next) break;
; #pragma unroll
;         for (int a = 0; a < 2; ++a)
; #pragma unroll
;             for (int b = 0; b < 2; ++b)
; #pragma unroll
;                 for (int m = 0; m < 4; ++m)
; #pragma unroll
;                     for (int n = 0; n < 2; ++n) acc[a][b][m][n] = (f32x4){0.f, 0.f, 0.f, 0.f};
;         cur = nxt; cA = nA; cB = nB; ++ui;
.LBB0_455:
	v_mov_b32_e32 v2, 0
	s_mov_b32 s4, s6
	s_mov_b32 s18, s75
	s_mov_b32 s54, s49
	v_mov_b32_e32 v3, v2
	v_mov_b32_e32 v4, v2
	v_mov_b32_e32 v5, v2
	v_mov_b32_e32 v6, v2
	v_mov_b32_e32 v7, v2
	v_mov_b32_e32 v8, v2
	v_mov_b32_e32 v9, v2
	v_mov_b32_e32 v10, v2
	v_mov_b32_e32 v11, v2
	v_mov_b32_e32 v12, v2
	v_mov_b32_e32 v13, v2
	v_mov_b32_e32 v14, v2
	v_mov_b32_e32 v15, v2
	v_mov_b32_e32 v16, v2
	v_mov_b32_e32 v17, v2
	v_mov_b32_e32 v18, v2
	v_mov_b32_e32 v19, v2
	v_mov_b32_e32 v20, v2
	v_mov_b32_e32 v21, v2
	v_mov_b32_e32 v22, v2
	v_mov_b32_e32 v23, v2
	v_mov_b32_e32 v24, v2
	v_mov_b32_e32 v25, v2
	v_mov_b32_e32 v26, v2
	v_mov_b32_e32 v27, v2
	v_mov_b32_e32 v28, v2
	v_mov_b32_e32 v29, v2
	v_mov_b32_e32 v30, v2
	v_mov_b32_e32 v31, v2
	v_mov_b32_e32 v32, v2
	v_mov_b32_e32 v33, v2
	v_mov_b32_e32 v34, v2
	v_mov_b32_e32 v35, v2
	v_mov_b32_e32 v36, v2
	v_mov_b32_e32 v37, v2
	v_mov_b32_e32 v38, v2
	v_mov_b32_e32 v39, v2
	v_mov_b32_e32 v40, v2
	v_mov_b32_e32 v41, v2
	v_mov_b32_e32 v42, v2
	v_mov_b32_e32 v43, v2
	v_mov_b32_e32 v44, v2
	v_mov_b32_e32 v45, v2
	v_mov_b32_e32 v46, v2
	v_mov_b32_e32 v47, v2
	v_mov_b32_e32 v48, v2
	v_mov_b32_e32 v49, v2
	v_mov_b32_e32 v50, v2
	v_mov_b32_e32 v51, v2
	v_mov_b32_e32 v52, v2
	v_mov_b32_e32 v53, v2
	v_mov_b32_e32 v54, v2
	v_mov_b32_e32 v55, v2
	v_mov_b32_e32 v56, v2
	v_mov_b32_e32 v57, v2
	v_mov_b32_e32 v58, v2
	v_mov_b32_e32 v59, v2
	v_mov_b32_e32 v60, v2
	v_mov_b32_e32 v61, v2
	v_mov_b32_e32 v62, v2
	v_mov_b32_e32 v63, v2
	v_mov_b32_e32 v64, v2
	v_mov_b32_e32 v65, v2
	v_mov_b32_e32 v66, v2
	v_mov_b32_e32 v67, v2
	v_mov_b32_e32 v68, v2
	v_mov_b32_e32 v69, v2
	v_mov_b32_e32 v70, v2
	v_mov_b32_e32 v71, v2
	v_mov_b32_e32 v72, v2
	v_mov_b32_e32 v73, v2
	v_mov_b32_e32 v74, v2
	v_mov_b32_e32 v75, v2
	v_mov_b32_e32 v76, v2
	v_mov_b32_e32 v77, v2
	v_mov_b32_e32 v78, v2
	v_mov_b32_e32 v79, v2
	v_mov_b32_e32 v80, v2
	v_mov_b32_e32 v81, v2
	v_mov_b32_e32 v82, v2
	v_mov_b32_e32 v83, v2
	v_mov_b32_e32 v84, v2
	v_mov_b32_e32 v85, v2
	v_mov_b32_e32 v86, v2
	v_mov_b32_e32 v87, v2
	v_mov_b32_e32 v88, v2
	v_mov_b32_e32 v89, v2
	v_mov_b32_e32 v90, v2
	v_mov_b32_e32 v91, v2
	v_mov_b32_e32 v92, v2
	v_mov_b32_e32 v93, v2
	v_mov_b32_e32 v94, v2
	v_mov_b32_e32 v95, v2
	v_mov_b32_e32 v96, v2
	v_mov_b32_e32 v97, v2
	v_mov_b32_e32 v98, v2
	v_mov_b32_e32 v99, v2
	v_mov_b32_e32 v100, v2
	v_mov_b32_e32 v101, v2
	v_mov_b32_e32 v102, v2
	v_mov_b32_e32 v103, v2
	v_mov_b32_e32 v104, v2
	v_mov_b32_e32 v105, v2
	v_mov_b32_e32 v106, v2
	v_mov_b32_e32 v107, v2
	v_mov_b32_e32 v108, v2
	v_mov_b32_e32 v109, v2
	v_mov_b32_e32 v110, v2
	v_mov_b32_e32 v111, v2
	v_mov_b32_e32 v112, v2
	v_mov_b32_e32 v113, v2
	v_mov_b32_e32 v114, v2
	v_mov_b32_e32 v115, v2
	v_mov_b32_e32 v116, v2
	v_mov_b32_e32 v117, v2
	v_mov_b32_e32 v118, v2
	v_mov_b32_e32 v119, v2
	v_mov_b32_e32 v120, v2
	v_mov_b32_e32 v121, v2
	v_mov_b32_e32 v122, v2
	v_mov_b32_e32 v123, v2
	v_mov_b32_e32 v124, v2
	v_mov_b32_e32 v125, v2
	v_mov_b32_e32 v126, v2
	v_mov_b32_e32 v127, v2
	v_mov_b32_e32 v128, v2
	v_mov_b32_e32 v129, v2
	s_andn2_b64 vcc, exec, s[8:9]
	s_mov_b64 s[12:13], s[10:11]
	s_cbranch_vccz .LBB0_517
	s_cmpk_gt_u32 s88, 0xff
	s_cbranch_scc0 .LBB0_456
	s_barrier

; template <class Epi, class Sched>
; __device__ __forceinline__ void gemm_phase(LAS unsigned char* lds, const int K, const int lda, const int ldb, const Sched& S, const Epi& E) {
;     ...
;         }
;         if constexpr (GATHER) { Unit n2; if (has_next && S.next(ui + 2, n2)) ld_ix(n2.pm, ix1); }
;         if constexpr (!Epi::AFTER_DRAIN) E(acc, cur, wr, wc, fr, fq);
.LBB0_488:
	s_cmpk_gt_u32 s88, 0xff
	s_cbranch_scc1 .Lgx_b_pre
	s_barrier

; #define PG8_WAIT_V(n) asm volatile("s_waitcnt vmcnt(" #n ")" ::: "memory")
; #define PG8_BAR __builtin_amdgcn_s_barrier()
; template <class Epi, class Sched>
; __device__ __forceinline__ void gemm_phase(LAS unsigned char* lds, const int K, const int lda, const int ldb, const Sched& S, const Epi& E) {
;     ...
;     PG8_WAIT_V(0);
;     if (wr == 0) PG8_BAR;
;     PG8_BAR;
.LBB0_517:
	s_waitcnt vmcnt(0)
.LBB0_519:
	v_readlane_b32 s54, v253, 13
	v_readlane_b32 s66, v253, 17
	v_readlane_b32 s75, v253, 6
	v_readlane_b32 s55, v253, 14
	v_readlane_b32 s67, v253, 18
	v_readlane_b32 s69, v253, 21
	s_movk_i32 s62, 0x14ff
	s_mov_b32 s68, 0x48000
	s_movk_i32 s45, 0x3fff
	s_mov_b32 s47, s94
	s_barrier

; #define PG8_STAGE(bufoff, gbase, voff) do { _Pragma("unroll") for (int _i = 0; _i < 2; ++_i) \
;         __builtin_amdgcn_global_load_lds((const unsigned*)((const char*)(gbase) + (voff)[_i]), (LAS unsigned*)(lds + (bufoff) + ldsw + _i * 8192), 16, 0, 0); } while (0)
; #define PG8_STAGE_A(bufoff, gbase, h, vv) do { if constexpr (GATHER) { _Pragma("unroll") for (int _i = 0; _i < 2; ++_i) \
;         __builtin_amdgcn_global_load_lds((const unsigned*)((const char*)(gbase) + (vv)[h][_i]), (LAS unsigned*)(lds + (bufoff) + ldsw + _i * 8192), 16, 0, 0); } \
;         else { PG8_STAGE(bufoff, (gbase) + (h) * hstepA, voffA); } } while (0)
; #define PG8_LDA(dst, b, h) do { _Pragma("unroll") for (int m = 0; m < 4; ++m) _Pragma("unroll") for (int k = 0; k < 2; ++k) dst[m][k] = *(const LAS bf16x8*)(lds + PG8_SA(b, h) + aoff + m * 2048 + k * 1024); } while (0)
; #define PG8_WAIT_V(n) asm volatile("s_waitcnt vmcnt(" #n ")" ::: "memory")
; #define PG8_WAIT_L(n) asm volatile("s_waitcnt lgkmcnt(" #n ")" ::: "memory")
; template <class Epi, class Sched>
; __device__ __forceinline__ void gemm_phase(LAS unsigned char* lds, const int K, const int lda, const int ldb, const Sched& S, const Epi& E) {
;     ...
;         for (int t = 0; t < nt; t += 2) {
;             const bool last = (t == nt - 2);
;             const char* a1 = cA + (size_t)(t + 1) * kstep;
;             const char* a2 = last ? nA : cA + (size_t)(t + 2) * kstep; const char* b2 = last ? nB : cB + (size_t)(t + 2) * kstep;
;             const char* a3 = a2 + kstep; const char* b3 = b2 + kstep;
;             PG8_LDB(B0, 0, 0); PG8_SCHED; PG8_LDA(At, 0, 0); PG8_STAGE_A(PG8_SA(1, 1), a1, 1, vcur);
;             if constexpr (GATHER) { if (last) {
; #pragma unroll
;                 for (int h = 0; h < 2; ++h)
; #pragma unroll
;                     for (int i = 0; i < 2; ++i) vcur[h][i] = vnxt[h][i]; } }
;             PG8_WAIT_L(8); PG8_BAR; PG8_WAIT_L(0); PG8_MMA(0, 0, At, B0); PG8_BAR; PG8_SCHED;
;             PG8_LDB(B1, 0, 1); PG8_STAGE(PG8_SB(0, 0), b2, voffB);
;             PG8_BAR; PG8_WAIT_L(0); PG8_MMA(0, 1, At, B1); PG8_BAR;
;             PG8_LDA(At, 0, 1); PG8_STAGE_A(PG8_SA(0, 0), a2, 0, vcur);
;             PG8_BAR; PG8_WAIT_L(0); PG8_MMA(1, 0, At, B0); PG8_BAR; PG8_SCHED;
;             PG8_STAGE(PG8_SB(0, 1), b2 + hstepB, voffB);
;             PG8_WAIT_V(6); PG8_BAR; PG8_MMA(1, 1, At, B1); PG8_BAR;
.LBB0_881:
	s_add_u32 s2, s14, 0xfffc0080
	s_addc_u32 s3, s15, -1
	s_add_i32 s20, 0, 0x10000
	v_add_u32_e32 v140, s20, v143
	ds_read_b128 v[146:149], v140
	ds_read_b128 v[150:153], v140 offset:1024
	ds_read_b128 v[154:157], v140 offset:2048
	ds_read_b128 v[158:161], v140 offset:3072
	s_cmp_eq_u32 s53, 12
	s_cselect_b32 s19, s9, s3
	s_cselect_b32 s18, s8, s2
	s_cselect_b32 s17, s11, s7
	s_cselect_b32 s16, s10, s5
	v_lshl_add_u64 v[140:141], s[14:15], 0, v[136:137]
	s_add_i32 m0, s13, 0xc000
	ds_read_b128 v[162:165], v145
	ds_read_b128 v[166:169], v145 offset:1024
	ds_read_b128 v[170:173], v145 offset:2048
	ds_read_b128 v[174:177], v145 offset:3072
	ds_read_b128 v[178:181], v145 offset:4096
	ds_read_b128 v[182:185], v145 offset:5120
	ds_read_b128 v[186:189], v145 offset:6144
	ds_read_b128 v[190:193], v145 offset:7168
	global_load_lds_dwordx4 v[140:141], off
	v_lshl_add_u64 v[140:141], s[14:15], 0, v[138:139]
	s_add_i32 m0, s13, 0xe000
	s_nop 0
	global_load_lds_dwordx4 v[140:141], off
	s_waitcnt lgkmcnt(8)
	s_barrier
	s_waitcnt lgkmcnt(0)
	s_setprio 1
	s_waitcnt lgkmcnt(0)
	v_mfma_f32_16x16x32_bf16 v[126:129], v[146:149], v[162:165], v[126:129]
	v_mfma_f32_16x16x32_bf16 v[118:121], v[154:157], v[162:165], v[118:121]
	v_mfma_f32_16x16x32_bf16 v[110:113], v[146:149], v[170:173], v[110:113]
	v_mfma_f32_16x16x32_bf16 v[102:105], v[154:157], v[170:173], v[102:105]
	v_mfma_f32_16x16x32_bf16 v[94:97], v[146:149], v[178:181], v[94:97]
	v_mfma_f32_16x16x32_bf16 v[86:89], v[154:157], v[178:181], v[86:89]
	v_mfma_f32_16x16x32_bf16 v[78:81], v[146:149], v[186:189], v[78:81]
	v_mfma_f32_16x16x32_bf16 v[70:73], v[154:157], v[186:189], v[70:73]
	v_mfma_f32_16x16x32_bf16 v[126:129], v[150:153], v[166:169], v[126:129]
	v_mfma_f32_16x16x32_bf16 v[118:121], v[158:161], v[166:169], v[118:121]
	v_mfma_f32_16x16x32_bf16 v[110:113], v[150:153], v[174:177], v[110:113]
	v_mfma_f32_16x16x32_bf16 v[102:105], v[158:161], v[174:177], v[102:105]
	v_mfma_f32_16x16x32_bf16 v[94:97], v[150:153], v[182:185], v[94:97]
	v_mfma_f32_16x16x32_bf16 v[86:89], v[158:161], v[182:185], v[86:89]
	v_mfma_f32_16x16x32_bf16 v[78:81], v[150:153], v[190:193], v[78:81]
	v_mfma_f32_16x16x32_bf16 v[70:73], v[158:161], v[190:193], v[70:73]
	s_setprio 0
	s_barrier
	s_add_i32 s2, 0, 0x14000
	v_add_u32_e32 v140, s2, v143
	s_add_i32 s3, s20, s43
	ds_read_b128 v[216:219], v140
	ds_read_b128 v[220:223], v140 offset:1024
	ds_read_b128 v[224:227], v140 offset:2048
	ds_read_b128 v[228:231], v140 offset:3072
	v_lshl_add_u64 v[140:141], s[16:17], 0, v[0:1]
	s_mov_b32 m0, s3
	v_lshl_add_u64 v[194:195], s[16:17], 0, v[134:135]
	global_load_lds_dwordx4 v[140:141], off
	s_add_i32 m0, s3, 0x2000
	s_nop 0
	global_load_lds_dwordx4 v[194:195], off
	s_barrier
	s_waitcnt lgkmcnt(0)
	s_setprio 1
	s_waitcnt lgkmcnt(0)
	v_mfma_f32_16x16x32_bf16 v[122:125], v[216:219], v[162:165], v[122:125]
	v_mfma_f32_16x16x32_bf16 v[114:117], v[224:227], v[162:165], v[114:117]
	v_mfma_f32_16x16x32_bf16 v[106:109], v[216:219], v[170:173], v[106:109]
	v_mfma_f32_16x16x32_bf16 v[98:101], v[224:227], v[170:173], v[98:101]
	v_mfma_f32_16x16x32_bf16 v[90:93], v[216:219], v[178:181], v[90:93]
	v_mfma_f32_16x16x32_bf16 v[82:85], v[224:227], v[178:181], v[82:85]
	v_mfma_f32_16x16x32_bf16 v[74:77], v[216:219], v[186:189], v[74:77]
	v_mfma_f32_16x16x32_bf16 v[66:69], v[224:227], v[186:189], v[66:69]
	v_mfma_f32_16x16x32_bf16 v[122:125], v[220:223], v[166:169], v[122:125]
	v_mfma_f32_16x16x32_bf16 v[114:117], v[228:231], v[166:169], v[114:117]
	v_mfma_f32_16x16x32_bf16 v[106:109], v[220:223], v[174:177], v[106:109]
	v_mfma_f32_16x16x32_bf16 v[98:101], v[228:231], v[174:177], v[98:101]
	v_mfma_f32_16x16x32_bf16 v[90:93], v[220:223], v[182:185], v[90:93]
	v_mfma_f32_16x16x32_bf16 v[82:85], v[228:231], v[182:185], v[82:85]
	v_mfma_f32_16x16x32_bf16 v[74:77], v[220:223], v[190:193], v[74:77]
	v_mfma_f32_16x16x32_bf16 v[66:69], v[228:231], v[190:193], v[66:69]
	s_setprio 0
	s_mov_b32 m0, s13
	v_lshl_add_u64 v[214:215], s[18:19], 0, v[130:131]
	s_barrier
	ds_read_b128 v[162:165], v145 offset:16384
	ds_read_b128 v[166:169], v145 offset:17408
	ds_read_b128 v[170:173], v145 offset:18432
	ds_read_b128 v[174:177], v145 offset:19456
	ds_read_b128 v[178:181], v145 offset:20480
	ds_read_b128 v[182:185], v145 offset:21504
	ds_read_b128 v[186:189], v145 offset:22528
	ds_read_b128 v[190:193], v145 offset:23552
	global_load_lds_dwordx4 v[214:215], off
	v_lshl_add_u64 v[232:233], s[18:19], 0, v[132:133]
	s_mov_b32 m0, s44
	s_nop 0
	global_load_lds_dwordx4 v[232:233], off
	s_barrier
	s_waitcnt lgkmcnt(0)
	s_setprio 1
	s_waitcnt lgkmcnt(0)
	v_mfma_f32_16x16x32_bf16 v[62:65], v[146:149], v[162:165], v[62:65]
	v_mfma_f32_16x16x32_bf16 v[54:57], v[154:157], v[162:165], v[54:57]
	v_mfma_f32_16x16x32_bf16 v[46:49], v[146:149], v[170:173], v[46:49]
	v_mfma_f32_16x16x32_bf16 v[38:41], v[154:157], v[170:173], v[38:41]
	v_mfma_f32_16x16x32_bf16 v[30:33], v[146:149], v[178:181], v[30:33]
	v_mfma_f32_16x16x32_bf16 v[22:25], v[154:157], v[178:181], v[22:25]
	v_mfma_f32_16x16x32_bf16 v[14:17], v[146:149], v[186:189], v[14:17]
	v_mfma_f32_16x16x32_bf16 v[6:9], v[154:157], v[186:189], v[6:9]
	v_mfma_f32_16x16x32_bf16 v[62:65], v[150:153], v[166:169], v[62:65]
	v_mfma_f32_16x16x32_bf16 v[54:57], v[158:161], v[166:169], v[54:57]
	v_mfma_f32_16x16x32_bf16 v[46:49], v[150:153], v[174:177], v[46:49]
	v_mfma_f32_16x16x32_bf16 v[38:41], v[158:161], v[174:177], v[38:41]
	v_mfma_f32_16x16x32_bf16 v[30:33], v[150:153], v[182:185], v[30:33]
	v_mfma_f32_16x16x32_bf16 v[22:25], v[158:161], v[182:185], v[22:25]
	v_mfma_f32_16x16x32_bf16 v[14:17], v[150:153], v[190:193], v[14:17]
	v_mfma_f32_16x16x32_bf16 v[6:9], v[158:161], v[190:193], v[6:9]
	s_setprio 0
	s_barrier
; #define PG8_STAGE(bufoff, gbase, voff) do { _Pragma("unroll") for (int _i = 0; _i < 2; ++_i) \
;         __builtin_amdgcn_global_load_lds((const unsigned*)((const char*)(gbase) + (voff)[_i]), (LAS unsigned*)(lds + (bufoff) + ldsw + _i * 8192), 16, 0, 0); } while (0)
; #define PG8_STAGE_A(bufoff, gbase, h, vv) do { if constexpr (GATHER) { _Pragma("unroll") for (int _i = 0; _i < 2; ++_i) \
;         __builtin_amdgcn_global_load_lds((const unsigned*)((const char*)(gbase) + (vv)[h][_i]), (LAS unsigned*)(lds + (bufoff) + ldsw + _i * 8192), 16, 0, 0); } \
;         else { PG8_STAGE(bufoff, (gbase) + (h) * hstepA, voffA); } } while (0)
; #define PG8_LDA(dst, b, h) do { _Pragma("unroll") for (int m = 0; m < 4; ++m) _Pragma("unroll") for (int k = 0; k < 2; ++k) dst[m][k] = *(const LAS bf16x8*)(lds + PG8_SA(b, h) + aoff + m * 2048 + k * 1024); } while (0)
; #define PG8_LDB(dst, b, h) do { _Pragma("unroll") for (int n = 0; n < 2; ++n) _Pragma("unroll") for (int k = 0; k < 2; ++k) dst[n][k] = *(const LAS bf16x8*)(lds + PG8_SB(b, h) + boff + n * 2048 + k * 1024); } while (0)
; #define PG8_MMA(ai, bj, At, Bt) do { __builtin_amdgcn_s_setprio(1); _Pragma("unroll") for (int m = 0; m < 4; ++m) _Pragma("unroll") for (int n = 0; n < 2; ++n) _Pragma("unroll") for (int k = 0; k < 2; ++k) \
;         acc[ai][bj][m][n] = __builtin_amdgcn_mfma_f32_16x16x32_bf16(Bt[n][k], At[m][k], acc[ai][bj][m][n], 0, 0, 0); __builtin_amdgcn_s_setprio(0); } while (0)
; #define PG8_BAR __builtin_amdgcn_s_barrier()
; template <class Epi, class Sched>
; __device__ __forceinline__ void gemm_phase(LAS unsigned char* lds, const int K, const int lda, const int ldb, const Sched& S, const Epi& E) {
;     ...
;             PG8_WAIT_V(6); PG8_BAR; PG8_MMA(1, 1, At, B1); PG8_BAR;
;             PG8_LDB(B0, 1, 0); PG8_SCHED; PG8_LDA(At, 1, 0); PG8_STAGE_A(PG8_SA(0, 1), a2, 1, vcur);
;             PG8_WAIT_L(8); PG8_BAR; PG8_WAIT_L(0); PG8_MMA(0, 0, At, B0); PG8_BAR; PG8_SCHED;
;             PG8_LDB(B1, 1, 1); PG8_STAGE(PG8_SB(1, 0), b3, voffB);
;             PG8_BAR; PG8_WAIT_L(0); PG8_MMA(0, 1, At, B1); PG8_BAR;
;             PG8_LDA(At, 1, 1); PG8_STAGE_A(PG8_SA(1, 0), a3, 0, vcur);
;             PG8_BAR; PG8_WAIT_L(0); PG8_MMA(1, 0, At, B0); PG8_BAR; PG8_SCHED;
;             PG8_STAGE(PG8_SB(1, 1), b3 + hstepB, voffB);
;             PG8_WAIT_V(6); PG8_BAR; PG8_MMA(1, 1, At, B1); PG8_BAR;
	s_add_u32 s54, s16, 0x40000
	s_addc_u32 s55, s17, 0
	s_add_i32 s2, s2, s43
	v_lshl_add_u64 v[146:147], s[54:55], 0, v[0:1]
	s_mov_b32 m0, s2
	s_nop 0
	global_load_lds_dwordx4 v[146:147], off
	v_lshl_add_u64 v[146:147], s[54:55], 0, v[134:135]
	s_add_i32 m0, s2, 0x2000
	s_nop 0
	global_load_lds_dwordx4 v[146:147], off
	s_waitcnt vmcnt(6)
	s_barrier
	s_setprio 1
	v_mfma_f32_16x16x32_bf16 v[58:61], v[216:219], v[162:165], v[58:61]
	v_mfma_f32_16x16x32_bf16 v[50:53], v[224:227], v[162:165], v[50:53]
	v_mfma_f32_16x16x32_bf16 v[42:45], v[216:219], v[170:173], v[42:45]
	v_mfma_f32_16x16x32_bf16 v[34:37], v[224:227], v[170:173], v[34:37]
	v_mfma_f32_16x16x32_bf16 v[26:29], v[216:219], v[178:181], v[26:29]
	v_mfma_f32_16x16x32_bf16 v[18:21], v[224:227], v[178:181], v[18:21]
	v_mfma_f32_16x16x32_bf16 v[10:13], v[216:219], v[186:189], v[10:13]
	v_mfma_f32_16x16x32_bf16 v[2:5], v[224:227], v[186:189], v[2:5]
	v_mfma_f32_16x16x32_bf16 v[58:61], v[220:223], v[166:169], v[58:61]
	v_mfma_f32_16x16x32_bf16 v[50:53], v[228:231], v[166:169], v[50:53]
	v_mfma_f32_16x16x32_bf16 v[42:45], v[220:223], v[174:177], v[42:45]
	v_mfma_f32_16x16x32_bf16 v[34:37], v[228:231], v[174:177], v[34:37]
	v_mfma_f32_16x16x32_bf16 v[26:29], v[220:223], v[182:185], v[26:29]
	v_mfma_f32_16x16x32_bf16 v[18:21], v[228:231], v[182:185], v[18:21]
	v_mfma_f32_16x16x32_bf16 v[10:13], v[220:223], v[190:193], v[10:13]
	v_mfma_f32_16x16x32_bf16 v[2:5], v[228:231], v[190:193], v[2:5]
	s_setprio 0
	s_add_i32 s2, 0, 0x18000
	v_add_u32_e32 v158, s2, v143
	s_barrier
	ds_read_b128 v[146:149], v158
	ds_read_b128 v[150:153], v158 offset:1024
	ds_read_b128 v[154:157], v158 offset:2048
	ds_read_b128 v[158:161], v158 offset:3072
	s_add_u32 s18, s18, 0x40000
	s_addc_u32 s19, s19, 0
	s_mov_b32 m0, s45
	v_lshl_add_u64 v[216:217], s[18:19], 0, v[130:131]
	ds_read_b128 v[162:165], v145 offset:32768
	ds_read_b128 v[166:169], v145 offset:33792
	ds_read_b128 v[170:173], v145 offset:34816
	ds_read_b128 v[174:177], v145 offset:35840
	ds_read_b128 v[178:181], v145 offset:36864
	ds_read_b128 v[182:185], v145 offset:37888
	ds_read_b128 v[186:189], v145 offset:38912
	ds_read_b128 v[190:193], v145 offset:39936
	global_load_lds_dwordx4 v[216:217], off
	v_lshl_add_u64 v[216:217], s[18:19], 0, v[132:133]
	s_mov_b32 m0, s46
	s_nop 0
	global_load_lds_dwordx4 v[216:217], off
	s_waitcnt lgkmcnt(8)
	s_barrier
	s_waitcnt lgkmcnt(0)
	s_setprio 1
	s_waitcnt lgkmcnt(0)
	v_mfma_f32_16x16x32_bf16 v[126:129], v[146:149], v[162:165], v[126:129]
	v_mfma_f32_16x16x32_bf16 v[118:121], v[154:157], v[162:165], v[118:121]
	v_mfma_f32_16x16x32_bf16 v[110:113], v[146:149], v[170:173], v[110:113]
	v_mfma_f32_16x16x32_bf16 v[102:105], v[154:157], v[170:173], v[102:105]
	v_mfma_f32_16x16x32_bf16 v[94:97], v[146:149], v[178:181], v[94:97]
	v_mfma_f32_16x16x32_bf16 v[86:89], v[154:157], v[178:181], v[86:89]
	v_mfma_f32_16x16x32_bf16 v[78:81], v[146:149], v[186:189], v[78:81]
	v_mfma_f32_16x16x32_bf16 v[70:73], v[154:157], v[186:189], v[70:73]
	v_mfma_f32_16x16x32_bf16 v[126:129], v[150:153], v[166:169], v[126:129]
	v_mfma_f32_16x16x32_bf16 v[118:121], v[158:161], v[166:169], v[118:121]
	v_mfma_f32_16x16x32_bf16 v[110:113], v[150:153], v[174:177], v[110:113]
	v_mfma_f32_16x16x32_bf16 v[102:105], v[158:161], v[174:177], v[102:105]
	v_mfma_f32_16x16x32_bf16 v[94:97], v[150:153], v[182:185], v[94:97]
	v_mfma_f32_16x16x32_bf16 v[86:89], v[158:161], v[182:185], v[86:89]
	v_mfma_f32_16x16x32_bf16 v[78:81], v[150:153], v[190:193], v[78:81]
	v_mfma_f32_16x16x32_bf16 v[70:73], v[158:161], v[190:193], v[70:73]
	s_setprio 0
	s_barrier
	s_add_i32 s3, 0, 0x1c000
	s_add_i32 s2, s2, s43
	v_add_u32_e32 v228, s3, v143
	v_lshl_add_u64 v[140:141], v[140:141], 0, s[64:65]
	s_mov_b32 m0, s2
	ds_read_b128 v[216:219], v228
	ds_read_b128 v[220:223], v228 offset:1024
	ds_read_b128 v[224:227], v228 offset:2048
	ds_read_b128 v[228:231], v228 offset:3072
	global_load_lds_dwordx4 v[140:141], off
	v_lshl_add_u64 v[140:141], v[194:195], 0, s[64:65]
	s_add_i32 m0, s2, 0x2000
	s_nop 0
	global_load_lds_dwordx4 v[140:141], off
	s_barrier
	s_waitcnt lgkmcnt(0)
	s_setprio 1
	s_waitcnt lgkmcnt(0)
	v_mfma_f32_16x16x32_bf16 v[122:125], v[216:219], v[162:165], v[122:125]
	v_mfma_f32_16x16x32_bf16 v[114:117], v[224:227], v[162:165], v[114:117]
	v_mfma_f32_16x16x32_bf16 v[106:109], v[216:219], v[170:173], v[106:109]
	v_mfma_f32_16x16x32_bf16 v[98:101], v[224:227], v[170:173], v[98:101]
	v_mfma_f32_16x16x32_bf16 v[90:93], v[216:219], v[178:181], v[90:93]
	v_mfma_f32_16x16x32_bf16 v[82:85], v[224:227], v[178:181], v[82:85]
	v_mfma_f32_16x16x32_bf16 v[74:77], v[216:219], v[186:189], v[74:77]
	v_mfma_f32_16x16x32_bf16 v[66:69], v[224:227], v[186:189], v[66:69]
	v_mfma_f32_16x16x32_bf16 v[122:125], v[220:223], v[166:169], v[122:125]
	v_mfma_f32_16x16x32_bf16 v[114:117], v[228:231], v[166:169], v[114:117]
	v_mfma_f32_16x16x32_bf16 v[106:109], v[220:223], v[174:177], v[106:109]
	v_mfma_f32_16x16x32_bf16 v[98:101], v[228:231], v[174:177], v[98:101]
	v_mfma_f32_16x16x32_bf16 v[90:93], v[220:223], v[182:185], v[90:93]
	v_mfma_f32_16x16x32_bf16 v[82:85], v[228:231], v[182:185], v[82:85]
	v_mfma_f32_16x16x32_bf16 v[74:77], v[220:223], v[190:193], v[74:77]
	v_mfma_f32_16x16x32_bf16 v[66:69], v[228:231], v[190:193], v[66:69]
	s_setprio 0
	s_mov_b32 m0, s47
	v_lshl_add_u64 v[140:141], v[214:215], 0, s[64:65]
	s_barrier
	ds_read_b128 v[162:165], v145 offset:49152
	ds_read_b128 v[166:169], v145 offset:50176
	ds_read_b128 v[170:173], v145 offset:51200
	ds_read_b128 v[174:177], v145 offset:52224
	ds_read_b128 v[178:181], v145 offset:53248
	ds_read_b128 v[182:185], v145 offset:54272
	ds_read_b128 v[186:189], v145 offset:55296
	ds_read_b128 v[190:193], v145 offset:56320
	global_load_lds_dwordx4 v[140:141], off
	v_lshl_add_u64 v[140:141], v[232:233], 0, s[64:65]
	s_mov_b32 m0, s48
	s_nop 0
	global_load_lds_dwordx4 v[140:141], off
	s_barrier
; __device__ __forceinline__ unsigned pk2(float lo, float hi) { unsigned r; asm("v_cvt_pk_bf16_f32 %0, %1, %2" : "=v"(r) : "v"(lo), "v"(hi)); return r; }
; __device__ __forceinline__ float silu_f(float v) { return v * __builtin_amdgcn_rcpf(1.f + __expf(-v)); }
; #define PG8_MMA(ai, bj, At, Bt) do { __builtin_amdgcn_s_setprio(1); _Pragma("unroll") for (int m = 0; m < 4; ++m) _Pragma("unroll") for (int n = 0; n < 2; ++n) _Pragma("unroll") for (int k = 0; k < 2; ++k) \
;         acc[ai][bj][m][n] = __builtin_amdgcn_mfma_f32_16x16x32_bf16(Bt[n][k], At[m][k], acc[ai][bj][m][n], 0, 0, 0); __builtin_amdgcn_s_setprio(0); } while (0)
; #define PG8_WAIT_V(n) asm volatile("s_waitcnt vmcnt(" #n ")" ::: "memory")
; #define PG8_BAR __builtin_amdgcn_s_barrier()
; template <class Epi, class Sched>
; __device__ __forceinline__ void gemm_phase(LAS unsigned char* lds, const int K, const int lda, const int ldb, const Sched& S, const Epi& E) {
;     ...
;             PG8_WAIT_V(6); PG8_BAR; PG8_MMA(1, 1, At, B1); PG8_BAR;
;         }
;         if constexpr (GATHER) { Unit n2; if (has_next && S.next(ui + 2, n2)) ld_ix(n2.pm, ix1); }
;         if constexpr (!Epi::AFTER_DRAIN) E(acc, cur, wr, wc, fr, fq);
;     __device__ __forceinline__ void operator()(const Acc& acc, const Unit& u, int wr, int wc, int fr, int fq) const {
;         const int row0 = u.pm * BM + wr * 64 + fr, col0 = u.pn * HALF + wc * 32 + 8 * fq;
; #pragma unroll
;         for (int ai = 0; ai < 2; ++ai)
; #pragma unroll
;             for (int m = 0; m < 4; ++m) { bf16_t* rp = Hd + (size_t)(row0 + ai * HALF + m * 16) * DFF + col0;
;                 float h[8];
; #pragma unroll
;                 for (int n = 0; n < 2; ++n)
; #pragma unroll
;                     for (int e = 0; e < 4; ++e) { const float g = acc[ai][0][m][n][e], up = acc[ai][1][m][n][e]; h[4 * n + e] = silu_f(g) * up; }
;                 u32x4 o; o.x = pk2(h[0], h[1]); o.y = pk2(h[2], h[3]); o.z = pk2(h[4], h[5]); o.w = pk2(h[6], h[7]);
;                 *(u32x4*)rp = o; }
	s_waitcnt lgkmcnt(0)
	s_setprio 1
	s_waitcnt lgkmcnt(0)
	v_mfma_f32_16x16x32_bf16 v[62:65], v[146:149], v[162:165], v[62:65]
	v_mfma_f32_16x16x32_bf16 v[54:57], v[154:157], v[162:165], v[54:57]
	v_mfma_f32_16x16x32_bf16 v[46:49], v[146:149], v[170:173], v[46:49]
	v_mfma_f32_16x16x32_bf16 v[38:41], v[154:157], v[170:173], v[38:41]
	v_mfma_f32_16x16x32_bf16 v[30:33], v[146:149], v[178:181], v[30:33]
	v_mfma_f32_16x16x32_bf16 v[22:25], v[154:157], v[178:181], v[22:25]
	v_mfma_f32_16x16x32_bf16 v[14:17], v[146:149], v[186:189], v[14:17]
	v_mfma_f32_16x16x32_bf16 v[6:9], v[154:157], v[186:189], v[6:9]
	v_mfma_f32_16x16x32_bf16 v[62:65], v[150:153], v[166:169], v[62:65]
	v_mfma_f32_16x16x32_bf16 v[54:57], v[158:161], v[166:169], v[54:57]
	v_mfma_f32_16x16x32_bf16 v[46:49], v[150:153], v[174:177], v[46:49]
	v_mfma_f32_16x16x32_bf16 v[38:41], v[158:161], v[174:177], v[38:41]
	v_mfma_f32_16x16x32_bf16 v[30:33], v[150:153], v[182:185], v[30:33]
	v_mfma_f32_16x16x32_bf16 v[22:25], v[158:161], v[182:185], v[22:25]
	v_mfma_f32_16x16x32_bf16 v[14:17], v[150:153], v[190:193], v[14:17]
	v_mfma_f32_16x16x32_bf16 v[6:9], v[158:161], v[190:193], v[6:9]
	s_setprio 0
	s_barrier
	s_add_u32 s16, s16, 0x40080
	s_addc_u32 s17, s17, 0
	s_add_i32 s2, s3, s43
	v_lshl_add_u64 v[140:141], s[16:17], 0, v[0:1]
	s_mov_b32 m0, s2
	s_nop 0
	global_load_lds_dwordx4 v[140:141], off
	v_lshl_add_u64 v[140:141], s[16:17], 0, v[134:135]
	s_add_i32 m0, s2, 0x2000
	s_nop 0
	global_load_lds_dwordx4 v[140:141], off
	s_waitcnt vmcnt(6)
	s_barrier
	s_setprio 1
	v_mfma_f32_16x16x32_bf16 v[58:61], v[216:219], v[162:165], v[58:61]
	v_mfma_f32_16x16x32_bf16 v[50:53], v[224:227], v[162:165], v[50:53]
	v_mfma_f32_16x16x32_bf16 v[42:45], v[216:219], v[170:173], v[42:45]
	v_mfma_f32_16x16x32_bf16 v[34:37], v[224:227], v[170:173], v[34:37]
	v_mfma_f32_16x16x32_bf16 v[26:29], v[216:219], v[178:181], v[26:29]
	v_mfma_f32_16x16x32_bf16 v[18:21], v[224:227], v[178:181], v[18:21]
	v_mfma_f32_16x16x32_bf16 v[10:13], v[216:219], v[186:189], v[10:13]
	v_mfma_f32_16x16x32_bf16 v[2:5], v[224:227], v[186:189], v[2:5]
	v_mfma_f32_16x16x32_bf16 v[58:61], v[220:223], v[166:169], v[58:61]
	v_mfma_f32_16x16x32_bf16 v[50:53], v[228:231], v[166:169], v[50:53]
	v_mfma_f32_16x16x32_bf16 v[42:45], v[220:223], v[174:177], v[42:45]
	v_mfma_f32_16x16x32_bf16 v[34:37], v[228:231], v[174:177], v[34:37]
	v_mfma_f32_16x16x32_bf16 v[26:29], v[220:223], v[182:185], v[26:29]
	v_mfma_f32_16x16x32_bf16 v[18:21], v[228:231], v[182:185], v[18:21]
	v_mfma_f32_16x16x32_bf16 v[10:13], v[220:223], v[190:193], v[10:13]
	v_mfma_f32_16x16x32_bf16 v[2:5], v[228:231], v[190:193], v[2:5]
	s_setprio 0
	s_add_i32 s53, s53, 2
	s_add_u32 s14, s14, 0x100
	s_addc_u32 s15, s15, 0
	s_add_u32 s5, s5, 0x100
	s_addc_u32 s7, s7, 0
	s_cmp_gt_u32 s53, 13
	s_barrier
	s_cbranch_scc0 .LBB0_881
	s_cmpk_gt_u32 s36, 0xff
	s_cbranch_scc1 .Lgx_a_pre
	s_barrier
.Lgx_a_pre:
	v_mul_f32_e32 v147, 0xbfb8aa3b, v126
	v_exp_f32_e32 v147, v147
	v_readlane_b32 s2, v250, 43
	v_lshl_or_b32 v148, s52, 7, v144
	v_readlane_b32 s3, v250, 44
	v_add_f32_e32 v147, 1.0, v147
	v_rcp_f32_e32 v147, v147
	v_lshl_add_u32 v146, s12, 8, v142
	v_ashrrev_i32_e32 v149, 31, v148
	v_mov_b64_e32 v[140:141], s[2:3]
	v_mul_f32_e32 v126, v126, v147
	v_mul_f32_e32 v122, v126, v122
	v_mul_f32_e32 v126, 0xbfb8aa3b, v127
	v_exp_f32_e32 v126, v126
	s_movk_i32 s2, 0x1c00
	v_mad_i64_i32 v[150:151], s[14:15], v146, s2, v[140:141]
	v_add_f32_e32 v126, 1.0, v126
	v_rcp_f32_e32 v126, v126
	v_readlane_b32 s54, v253, 13
	s_and_b64 vcc, exec, s[0:1]
	s_mov_b32 s52, s4
	v_mul_f32_e32 v126, v127, v126
	v_mul_f32_e32 v123, v126, v123
	v_mul_f32_e32 v126, 0xbfb8aa3b, v128
	v_exp_f32_e32 v126, v126
	s_mov_b32 s12, s6
	s_mov_b64 s[16:17], s[10:11]
	v_readlane_b32 s55, v253, 14
	v_add_f32_e32 v126, 1.0, v126
	v_rcp_f32_e32 v126, v126
	s_nop 0
	v_mul_f32_e32 v126, v128, v126
	v_mul_f32_e32 v124, v126, v124
	v_mul_f32_e32 v126, 0xbfb8aa3b, v129
	v_exp_f32_e32 v126, v126
	s_nop 0
	v_add_f32_e32 v126, 1.0, v126
	v_rcp_f32_e32 v126, v126
	s_nop 0
	v_mul_f32_e32 v126, v129, v126
	v_mul_f32_e32 v125, v126, v125
	v_mul_f32_e32 v126, 0xbfb8aa3b, v118
	v_exp_f32_e32 v126, v126
	s_nop 0
	v_add_f32_e32 v126, 1.0, v126
	v_rcp_f32_e32 v126, v126
	s_nop 0
	v_mul_f32_e32 v118, v118, v126
	v_mul_f32_e32 v118, v118, v114
	v_mul_f32_e32 v114, 0xbfb8aa3b, v119
	v_exp_f32_e32 v114, v114
	s_nop 0
	v_add_f32_e32 v114, 1.0, v114
	v_rcp_f32_e32 v114, v114
	s_nop 0
	v_mul_f32_e32 v114, v119, v114
	v_mul_f32_e32 v119, v114, v115
	v_mul_f32_e32 v114, 0xbfb8aa3b, v120
	v_exp_f32_e32 v114, v114
	v_cvt_pk_bf16_f32 v118, v118, v119
	s_nop 0
	v_add_f32_e32 v114, 1.0, v114
	v_rcp_f32_e32 v114, v114
	s_nop 0
	v_mul_f32_e32 v114, v120, v114
	v_mul_f32_e32 v126, v114, v116
	v_mul_f32_e32 v114, 0xbfb8aa3b, v121
	v_exp_f32_e32 v114, v114
	v_cvt_pk_bf16_f32 v116, v122, v123
	s_nop 0
	v_add_f32_e32 v114, 1.0, v114
	v_rcp_f32_e32 v114, v114
	s_nop 0
	v_mul_f32_e32 v114, v121, v114
	v_mul_f32_e32 v127, v114, v117
	v_lshlrev_b64 v[114:115], 1, v[148:149]
	v_lshl_add_u64 v[120:121], v[150:151], 0, v[114:115]
	v_cvt_pk_bf16_f32 v117, v124, v125
	v_cvt_pk_bf16_f32 v119, v126, v127
	global_store_dwordx4 v[120:121], v[116:119], off
	s_nop 1
	v_mul_f32_e32 v118, 0xbfb8aa3b, v110
	v_exp_f32_e32 v118, v118
	v_or_b32_e32 v116, 16, v146
	v_mad_i64_i32 v[116:117], s[14:15], v116, s2, v[140:141]
	v_add_f32_e32 v118, 1.0, v118
	v_rcp_f32_e32 v118, v118
	s_nop 0
	v_mul_f32_e32 v110, v110, v118
	v_mul_f32_e32 v106, v110, v106
	v_mul_f32_e32 v110, 0xbfb8aa3b, v111
	v_exp_f32_e32 v110, v110
	s_nop 0
	v_add_f32_e32 v110, 1.0, v110
	v_rcp_f32_e32 v110, v110
	s_nop 0
; __device__ __forceinline__ unsigned pk2(float lo, float hi) { unsigned r; asm("v_cvt_pk_bf16_f32 %0, %1, %2" : "=v"(r) : "v"(lo), "v"(hi)); return r; }
; __device__ __forceinline__ float silu_f(float v) { return v * __builtin_amdgcn_rcpf(1.f + __expf(-v)); }
;     __device__ __forceinline__ void operator()(const Acc& acc, const Unit& u, int wr, int wc, int fr, int fq) const {
;         const int row0 = u.pm * BM + wr * 64 + fr, col0 = u.pn * HALF + wc * 32 + 8 * fq;
; #pragma unroll
;         for (int ai = 0; ai < 2; ++ai)
; #pragma unroll
;             for (int m = 0; m < 4; ++m) { bf16_t* rp = Hd + (size_t)(row0 + ai * HALF + m * 16) * DFF + col0;
;                 float h[8];
; #pragma unroll
;                 for (int n = 0; n < 2; ++n)
; #pragma unroll
;                     for (int e = 0; e < 4; ++e) { const float g = acc[ai][0][m][n][e], up = acc[ai][1][m][n][e]; h[4 * n + e] = silu_f(g) * up; }
;                 u32x4 o; o.x = pk2(h[0], h[1]); o.y = pk2(h[2], h[3]); o.z = pk2(h[4], h[5]); o.w = pk2(h[6], h[7]);
;                 *(u32x4*)rp = o; }
	v_mul_f32_e32 v110, v111, v110
	v_mul_f32_e32 v107, v110, v107
	v_mul_f32_e32 v110, 0xbfb8aa3b, v112
	v_exp_f32_e32 v110, v110
	s_nop 0
	v_add_f32_e32 v110, 1.0, v110
	v_rcp_f32_e32 v110, v110
	s_nop 0
	v_mul_f32_e32 v110, v112, v110
	v_mul_f32_e32 v108, v110, v108
	v_mul_f32_e32 v110, 0xbfb8aa3b, v113
	v_exp_f32_e32 v110, v110
	s_nop 0
	v_add_f32_e32 v110, 1.0, v110
	v_rcp_f32_e32 v110, v110
	s_nop 0
	v_mul_f32_e32 v110, v113, v110
	v_mul_f32_e32 v109, v110, v109
	v_mul_f32_e32 v110, 0xbfb8aa3b, v102
	v_exp_f32_e32 v110, v110
	s_nop 0
	v_add_f32_e32 v110, 1.0, v110
	v_rcp_f32_e32 v110, v110
	s_nop 0
	v_mul_f32_e32 v102, v102, v110
	v_mul_f32_e32 v110, v102, v98
	v_mul_f32_e32 v98, 0xbfb8aa3b, v103
	v_exp_f32_e32 v98, v98
	s_nop 0
	v_add_f32_e32 v98, 1.0, v98
	v_rcp_f32_e32 v98, v98
	s_nop 0
	v_mul_f32_e32 v98, v103, v98
	v_mul_f32_e32 v111, v98, v99
	v_mul_f32_e32 v98, 0xbfb8aa3b, v104
	v_exp_f32_e32 v98, v98
	v_lshl_add_u64 v[102:103], v[116:117], 0, v[114:115]
	v_cvt_pk_bf16_f32 v99, v108, v109
	v_add_f32_e32 v98, 1.0, v98
	v_rcp_f32_e32 v98, v98
	s_nop 0
	v_mul_f32_e32 v98, v104, v98
	v_mul_f32_e32 v104, v98, v100
	v_mul_f32_e32 v98, 0xbfb8aa3b, v105
	v_exp_f32_e32 v98, v98
	v_cvt_pk_bf16_f32 v100, v110, v111
	s_nop 0
	v_add_f32_e32 v98, 1.0, v98
	v_rcp_f32_e32 v98, v98
	s_nop 0
	v_mul_f32_e32 v98, v105, v98
	v_mul_f32_e32 v101, v98, v101
	v_cvt_pk_bf16_f32 v98, v106, v107
	v_cvt_pk_bf16_f32 v101, v104, v101
	global_store_dwordx4 v[102:103], v[98:101], off
	s_nop 1
	v_mul_f32_e32 v100, 0xbfb8aa3b, v94
	v_exp_f32_e32 v100, v100
	v_or_b32_e32 v98, 32, v146
	v_mad_i64_i32 v[98:99], s[14:15], v98, s2, v[140:141]
	v_add_f32_e32 v100, 1.0, v100
	v_rcp_f32_e32 v100, v100
	s_nop 0
	v_mul_f32_e32 v94, v94, v100
	v_mul_f32_e32 v90, v94, v90
	v_mul_f32_e32 v94, 0xbfb8aa3b, v95
	v_exp_f32_e32 v94, v94
	s_nop 0
	v_add_f32_e32 v94, 1.0, v94
	v_rcp_f32_e32 v94, v94
	s_nop 0
	v_mul_f32_e32 v94, v95, v94
	v_mul_f32_e32 v91, v94, v91
	v_mul_f32_e32 v94, 0xbfb8aa3b, v96
	v_exp_f32_e32 v94, v94
	s_nop 0
	v_add_f32_e32 v94, 1.0, v94
	v_rcp_f32_e32 v94, v94
	s_nop 0
	v_mul_f32_e32 v94, v96, v94
	v_mul_f32_e32 v92, v94, v92
	v_mul_f32_e32 v94, 0xbfb8aa3b, v97
	v_exp_f32_e32 v94, v94
	s_nop 0
	v_add_f32_e32 v94, 1.0, v94
	v_rcp_f32_e32 v94, v94
	s_nop 0
	v_mul_f32_e32 v94, v97, v94
	v_mul_f32_e32 v93, v94, v93
	v_mul_f32_e32 v94, 0xbfb8aa3b, v86
	v_exp_f32_e32 v94, v94
	s_nop 0
	v_add_f32_e32 v94, 1.0, v94
	v_rcp_f32_e32 v94, v94
	s_nop 0
	v_mul_f32_e32 v86, v86, v94
	v_mul_f32_e32 v94, v86, v82
	v_mul_f32_e32 v82, 0xbfb8aa3b, v87
	v_exp_f32_e32 v82, v82
	s_nop 0
	v_add_f32_e32 v82, 1.0, v82
	v_rcp_f32_e32 v82, v82
	s_nop 0
	v_mul_f32_e32 v82, v87, v82
	v_mul_f32_e32 v95, v82, v83
	v_mul_f32_e32 v82, 0xbfb8aa3b, v88
	v_exp_f32_e32 v82, v82
	v_lshl_add_u64 v[86:87], v[98:99], 0, v[114:115]
	v_cvt_pk_bf16_f32 v83, v92, v93
	v_add_f32_e32 v82, 1.0, v82
	v_rcp_f32_e32 v82, v82
	s_nop 0
	v_mul_f32_e32 v82, v88, v82
	v_mul_f32_e32 v88, v82, v84
	v_mul_f32_e32 v82, 0xbfb8aa3b, v89
	v_exp_f32_e32 v82, v82
	v_cvt_pk_bf16_f32 v84, v94, v95
	s_nop 0
	v_add_f32_e32 v82, 1.0, v82
	v_rcp_f32_e32 v82, v82
	s_nop 0
	v_mul_f32_e32 v82, v89, v82
	v_mul_f32_e32 v85, v82, v85
	v_cvt_pk_bf16_f32 v82, v90, v91
	v_cvt_pk_bf16_f32 v85, v88, v85
	global_store_dwordx4 v[86:87], v[82:85], off
	s_nop 1
	v_mul_f32_e32 v84, 0xbfb8aa3b, v78
	v_exp_f32_e32 v84, v84
	v_or_b32_e32 v82, 48, v146
	v_mad_i64_i32 v[82:83], s[14:15], v82, s2, v[140:141]
	v_add_f32_e32 v84, 1.0, v84
	v_rcp_f32_e32 v84, v84
	s_nop 0
	v_mul_f32_e32 v78, v78, v84
	v_mul_f32_e32 v74, v78, v74
	v_mul_f32_e32 v78, 0xbfb8aa3b, v79
	v_exp_f32_e32 v78, v78
	s_nop 0
	v_add_f32_e32 v78, 1.0, v78
	v_rcp_f32_e32 v78, v78
	s_nop 0
	v_mul_f32_e32 v78, v79, v78
	v_mul_f32_e32 v75, v78, v75
	v_mul_f32_e32 v78, 0xbfb8aa3b, v80
	v_exp_f32_e32 v78, v78
	s_nop 0
	v_add_f32_e32 v78, 1.0, v78
	v_rcp_f32_e32 v78, v78
	s_nop 0
	v_mul_f32_e32 v78, v80, v78
	v_mul_f32_e32 v76, v78, v76
	v_mul_f32_e32 v78, 0xbfb8aa3b, v81
	v_exp_f32_e32 v78, v78
	s_nop 0
	v_add_f32_e32 v78, 1.0, v78
	v_rcp_f32_e32 v78, v78
	s_nop 0
	v_mul_f32_e32 v78, v81, v78
	v_mul_f32_e32 v77, v78, v77
	v_mul_f32_e32 v78, 0xbfb8aa3b, v70
	v_exp_f32_e32 v78, v78
	s_nop 0
	v_add_f32_e32 v78, 1.0, v78
	v_rcp_f32_e32 v78, v78
	s_nop 0
	v_mul_f32_e32 v70, v70, v78
	v_mul_f32_e32 v78, v70, v66
	v_mul_f32_e32 v66, 0xbfb8aa3b, v71
	v_exp_f32_e32 v66, v66
	s_nop 0
	v_add_f32_e32 v66, 1.0, v66
	v_rcp_f32_e32 v66, v66
	s_nop 0
	v_mul_f32_e32 v66, v71, v66
	v_mul_f32_e32 v79, v66, v67
	v_mul_f32_e32 v66, 0xbfb8aa3b, v72
	v_exp_f32_e32 v66, v66
	v_lshl_add_u64 v[70:71], v[82:83], 0, v[114:115]
	v_cvt_pk_bf16_f32 v67, v76, v77
	v_add_f32_e32 v66, 1.0, v66
	v_rcp_f32_e32 v66, v66
	s_nop 0
	v_mul_f32_e32 v66, v72, v66
	v_mul_f32_e32 v72, v66, v68
	v_mul_f32_e32 v66, 0xbfb8aa3b, v73
	v_exp_f32_e32 v66, v66
	v_cvt_pk_bf16_f32 v68, v78, v79
	s_nop 0
	v_add_f32_e32 v66, 1.0, v66
	v_rcp_f32_e32 v66, v66
	s_nop 0
	v_mul_f32_e32 v66, v73, v66
	v_mul_f32_e32 v69, v66, v69
	v_cvt_pk_bf16_f32 v66, v74, v75
	v_cvt_pk_bf16_f32 v69, v72, v69
	global_store_dwordx4 v[70:71], v[66:69], off
	s_nop 1
	v_mul_f32_e32 v68, 0xbfb8aa3b, v62
	v_exp_f32_e32 v68, v68
	v_add_u32_e32 v66, 0x80, v146
	v_mad_i64_i32 v[66:67], s[14:15], v66, s2, v[140:141]
	v_add_f32_e32 v68, 1.0, v68
	v_rcp_f32_e32 v68, v68
	s_nop 0
	v_mul_f32_e32 v62, v62, v68
	v_mul_f32_e32 v58, v62, v58
	v_mul_f32_e32 v62, 0xbfb8aa3b, v63
	v_exp_f32_e32 v62, v62
	s_nop 0
	v_add_f32_e32 v62, 1.0, v62
	v_rcp_f32_e32 v62, v62
	s_nop 0
	v_mul_f32_e32 v62, v63, v62
	v_mul_f32_e32 v59, v62, v59
	v_mul_f32_e32 v62, 0xbfb8aa3b, v64
	v_exp_f32_e32 v62, v62
; __device__ __forceinline__ unsigned pk2(float lo, float hi) { unsigned r; asm("v_cvt_pk_bf16_f32 %0, %1, %2" : "=v"(r) : "v"(lo), "v"(hi)); return r; }
; __device__ __forceinline__ float silu_f(float v) { return v * __builtin_amdgcn_rcpf(1.f + __expf(-v)); }
; #define PG8_WAIT_V(n) asm volatile("s_waitcnt vmcnt(" #n ")" ::: "memory")
; #define PG8_BAR __builtin_amdgcn_s_barrier()
; template <class Epi, class Sched>
; __device__ __forceinline__ void gemm_phase(LAS unsigned char* lds, const int K, const int lda, const int ldb, const Sched& S, const Epi& E) {
;     ...
;         if (!has_next) break;
; #pragma unroll
;         for (int a = 0; a < 2; ++a)
; #pragma unroll
;             for (int b = 0; b < 2; ++b)
; #pragma unroll
;                 for (int m = 0; m < 4; ++m)
; #pragma unroll
;                     for (int n = 0; n < 2; ++n) acc[a][b][m][n] = (f32x4){0.f, 0.f, 0.f, 0.f};
;         cur = nxt; cA = nA; cB = nB; ++ui;
;     }
;     PG8_WAIT_V(0);
;     if (wr == 0) PG8_BAR;
;     PG8_BAR;
;     __device__ __forceinline__ void operator()(const Acc& acc, const Unit& u, int wr, int wc, int fr, int fq) const {
;         const int row0 = u.pm * BM + wr * 64 + fr, col0 = u.pn * HALF + wc * 32 + 8 * fq;
; #pragma unroll
;         for (int ai = 0; ai < 2; ++ai)
; #pragma unroll
;             for (int m = 0; m < 4; ++m) { bf16_t* rp = Hd + (size_t)(row0 + ai * HALF + m * 16) * DFF + col0;
;                 float h[8];
; #pragma unroll
;                 for (int n = 0; n < 2; ++n)
; #pragma unroll
;                     for (int e = 0; e < 4; ++e) { const float g = acc[ai][0][m][n][e], up = acc[ai][1][m][n][e]; h[4 * n + e] = silu_f(g) * up; }
;                 u32x4 o; o.x = pk2(h[0], h[1]); o.y = pk2(h[2], h[3]); o.z = pk2(h[4], h[5]); o.w = pk2(h[6], h[7]);
;                 *(u32x4*)rp = o; }
	s_nop 0
	v_add_f32_e32 v62, 1.0, v62
	v_rcp_f32_e32 v62, v62
	s_nop 0
	v_mul_f32_e32 v62, v64, v62
	v_mul_f32_e32 v60, v62, v60
	v_mul_f32_e32 v62, 0xbfb8aa3b, v65
	v_exp_f32_e32 v62, v62
	s_nop 0
	v_add_f32_e32 v62, 1.0, v62
	v_rcp_f32_e32 v62, v62
	s_nop 0
	v_mul_f32_e32 v62, v65, v62
	v_mul_f32_e32 v61, v62, v61
	v_mul_f32_e32 v62, 0xbfb8aa3b, v54
	v_exp_f32_e32 v62, v62
	s_nop 0
	v_add_f32_e32 v62, 1.0, v62
	v_rcp_f32_e32 v62, v62
	s_nop 0
	v_mul_f32_e32 v54, v54, v62
	v_mul_f32_e32 v62, v54, v50
	v_mul_f32_e32 v50, 0xbfb8aa3b, v55
	v_exp_f32_e32 v50, v50
	s_nop 0
	v_add_f32_e32 v50, 1.0, v50
	v_rcp_f32_e32 v50, v50
	s_nop 0
	v_mul_f32_e32 v50, v55, v50
	v_mul_f32_e32 v63, v50, v51
	v_mul_f32_e32 v50, 0xbfb8aa3b, v56
	v_exp_f32_e32 v50, v50
	v_lshl_add_u64 v[54:55], v[66:67], 0, v[114:115]
	v_cvt_pk_bf16_f32 v51, v60, v61
	v_add_f32_e32 v50, 1.0, v50
	v_rcp_f32_e32 v50, v50
	s_nop 0
	v_mul_f32_e32 v50, v56, v50
	v_mul_f32_e32 v56, v50, v52
	v_mul_f32_e32 v50, 0xbfb8aa3b, v57
	v_exp_f32_e32 v50, v50
	v_cvt_pk_bf16_f32 v52, v62, v63
	s_nop 0
	v_add_f32_e32 v50, 1.0, v50
	v_rcp_f32_e32 v50, v50
	s_nop 0
	v_mul_f32_e32 v50, v57, v50
	v_mul_f32_e32 v53, v50, v53
	v_cvt_pk_bf16_f32 v50, v58, v59
	v_cvt_pk_bf16_f32 v53, v56, v53
	global_store_dwordx4 v[54:55], v[50:53], off
	s_nop 1
	v_mul_f32_e32 v52, 0xbfb8aa3b, v46
	v_exp_f32_e32 v52, v52
	v_add_u32_e32 v50, 0x90, v146
	v_mad_i64_i32 v[50:51], s[14:15], v50, s2, v[140:141]
	v_add_f32_e32 v52, 1.0, v52
	v_rcp_f32_e32 v52, v52
	s_nop 0
	v_mul_f32_e32 v46, v46, v52
	v_mul_f32_e32 v42, v46, v42
	v_mul_f32_e32 v46, 0xbfb8aa3b, v47
	v_exp_f32_e32 v46, v46
	s_nop 0
	v_add_f32_e32 v46, 1.0, v46
	v_rcp_f32_e32 v46, v46
	s_nop 0
	v_mul_f32_e32 v46, v47, v46
	v_mul_f32_e32 v43, v46, v43
	v_mul_f32_e32 v46, 0xbfb8aa3b, v48
	v_exp_f32_e32 v46, v46
	s_nop 0
	v_add_f32_e32 v46, 1.0, v46
	v_rcp_f32_e32 v46, v46
	s_nop 0
	v_mul_f32_e32 v46, v48, v46
	v_mul_f32_e32 v44, v46, v44
	v_mul_f32_e32 v46, 0xbfb8aa3b, v49
	v_exp_f32_e32 v46, v46
	s_nop 0
	v_add_f32_e32 v46, 1.0, v46
	v_rcp_f32_e32 v46, v46
	s_nop 0
	v_mul_f32_e32 v46, v49, v46
	v_mul_f32_e32 v45, v46, v45
	v_mul_f32_e32 v46, 0xbfb8aa3b, v38
	v_exp_f32_e32 v46, v46
	s_nop 0
	v_add_f32_e32 v46, 1.0, v46
	v_rcp_f32_e32 v46, v46
	s_nop 0
	v_mul_f32_e32 v38, v38, v46
	v_mul_f32_e32 v46, v38, v34
	v_mul_f32_e32 v34, 0xbfb8aa3b, v39
	v_exp_f32_e32 v34, v34
	s_nop 0
	v_add_f32_e32 v34, 1.0, v34
	v_rcp_f32_e32 v34, v34
	s_nop 0
	v_mul_f32_e32 v34, v39, v34
	v_mul_f32_e32 v47, v34, v35
	v_mul_f32_e32 v34, 0xbfb8aa3b, v40
	v_exp_f32_e32 v34, v34
	v_lshl_add_u64 v[38:39], v[50:51], 0, v[114:115]
	v_cvt_pk_bf16_f32 v35, v44, v45
	v_add_f32_e32 v34, 1.0, v34
	v_rcp_f32_e32 v34, v34
	s_nop 0
	v_mul_f32_e32 v34, v40, v34
	v_mul_f32_e32 v40, v34, v36
	v_mul_f32_e32 v34, 0xbfb8aa3b, v41
	v_exp_f32_e32 v34, v34
	v_cvt_pk_bf16_f32 v36, v46, v47
	s_nop 0
	v_add_f32_e32 v34, 1.0, v34
	v_rcp_f32_e32 v34, v34
	s_nop 0
	v_mul_f32_e32 v34, v41, v34
	v_mul_f32_e32 v37, v34, v37
	v_cvt_pk_bf16_f32 v34, v42, v43
	v_cvt_pk_bf16_f32 v37, v40, v37
	global_store_dwordx4 v[38:39], v[34:37], off
	s_nop 1
	v_mul_f32_e32 v36, 0xbfb8aa3b, v30
	v_exp_f32_e32 v36, v36
	v_add_u32_e32 v34, 0xa0, v146
	v_mad_i64_i32 v[34:35], s[14:15], v34, s2, v[140:141]
	v_add_f32_e32 v36, 1.0, v36
	v_rcp_f32_e32 v36, v36
	s_nop 0
	v_mul_f32_e32 v30, v30, v36
	v_mul_f32_e32 v26, v30, v26
	v_mul_f32_e32 v30, 0xbfb8aa3b, v31
	v_exp_f32_e32 v30, v30
	s_nop 0
	v_add_f32_e32 v30, 1.0, v30
	v_rcp_f32_e32 v30, v30
	s_nop 0
	v_mul_f32_e32 v30, v31, v30
	v_mul_f32_e32 v27, v30, v27
	v_mul_f32_e32 v30, 0xbfb8aa3b, v32
	v_exp_f32_e32 v30, v30
	s_nop 0
	v_add_f32_e32 v30, 1.0, v30
	v_rcp_f32_e32 v30, v30
	s_nop 0
	v_mul_f32_e32 v30, v32, v30
	v_mul_f32_e32 v28, v30, v28
	v_mul_f32_e32 v30, 0xbfb8aa3b, v33
	v_exp_f32_e32 v30, v30
	s_nop 0
	v_add_f32_e32 v30, 1.0, v30
	v_rcp_f32_e32 v30, v30
	s_nop 0
	v_mul_f32_e32 v30, v33, v30
	v_mul_f32_e32 v29, v30, v29
	v_mul_f32_e32 v30, 0xbfb8aa3b, v22
	v_exp_f32_e32 v30, v30
	s_nop 0
	v_add_f32_e32 v30, 1.0, v30
	v_rcp_f32_e32 v30, v30
	s_nop 0
	v_mul_f32_e32 v22, v22, v30
	v_mul_f32_e32 v30, v22, v18
	v_mul_f32_e32 v18, 0xbfb8aa3b, v23
	v_exp_f32_e32 v18, v18
	s_nop 0
	v_add_f32_e32 v18, 1.0, v18
	v_rcp_f32_e32 v18, v18
	s_nop 0
	v_mul_f32_e32 v18, v23, v18
	v_mul_f32_e32 v31, v18, v19
	v_mul_f32_e32 v18, 0xbfb8aa3b, v24
	v_exp_f32_e32 v18, v18
	v_lshl_add_u64 v[22:23], v[34:35], 0, v[114:115]
	v_cvt_pk_bf16_f32 v19, v28, v29
	v_add_f32_e32 v18, 1.0, v18
	v_rcp_f32_e32 v18, v18
	s_nop 0
	v_mul_f32_e32 v18, v24, v18
	v_mul_f32_e32 v24, v18, v20
	v_mul_f32_e32 v18, 0xbfb8aa3b, v25
	v_exp_f32_e32 v18, v18
	v_cvt_pk_bf16_f32 v20, v30, v31
	s_nop 0
	v_add_f32_e32 v18, 1.0, v18
	v_rcp_f32_e32 v18, v18
	s_nop 0
	v_mul_f32_e32 v18, v25, v18
	v_mul_f32_e32 v21, v18, v21
	v_cvt_pk_bf16_f32 v18, v26, v27
	v_cvt_pk_bf16_f32 v21, v24, v21
	global_store_dwordx4 v[22:23], v[18:21], off
	s_nop 1
	v_mul_f32_e32 v20, 0xbfb8aa3b, v14
	v_exp_f32_e32 v20, v20
	v_add_u32_e32 v18, 0xb0, v146
	v_mad_i64_i32 v[18:19], s[14:15], v18, s2, v[140:141]
	v_add_f32_e32 v20, 1.0, v20
	v_rcp_f32_e32 v20, v20
	s_mov_b64 s[14:15], s[8:9]
	v_mul_f32_e32 v14, v14, v20
	v_mul_f32_e32 v10, v14, v10
	v_mul_f32_e32 v14, 0xbfb8aa3b, v15
	v_exp_f32_e32 v14, v14
	s_nop 0
	v_add_f32_e32 v14, 1.0, v14
	v_rcp_f32_e32 v14, v14
	s_nop 0
	v_mul_f32_e32 v14, v15, v14
	v_mul_f32_e32 v11, v14, v11
	v_mul_f32_e32 v14, 0xbfb8aa3b, v16
	v_exp_f32_e32 v14, v14
	s_nop 0
	v_add_f32_e32 v14, 1.0, v14
	v_rcp_f32_e32 v14, v14
	s_nop 0
	v_mul_f32_e32 v14, v16, v14
	v_mul_f32_e32 v12, v14, v12
	v_mul_f32_e32 v14, 0xbfb8aa3b, v17
	v_exp_f32_e32 v14, v14
	s_nop 0
	v_add_f32_e32 v14, 1.0, v14
	v_rcp_f32_e32 v14, v14
	s_nop 0
	v_mul_f32_e32 v14, v17, v14
	v_mul_f32_e32 v13, v14, v13
	v_mul_f32_e32 v14, 0xbfb8aa3b, v6
	v_exp_f32_e32 v14, v14
	s_nop 0
	v_add_f32_e32 v14, 1.0, v14
	v_rcp_f32_e32 v14, v14
	s_nop 0
	v_mul_f32_e32 v6, v6, v14
	v_mul_f32_e32 v14, v6, v2
	v_mul_f32_e32 v2, 0xbfb8aa3b, v7
	v_exp_f32_e32 v2, v2
	s_nop 0
	v_add_f32_e32 v2, 1.0, v2
	v_rcp_f32_e32 v2, v2
	s_nop 0
	v_mul_f32_e32 v2, v7, v2
	v_mul_f32_e32 v15, v2, v3
	v_mul_f32_e32 v2, 0xbfb8aa3b, v8
	v_exp_f32_e32 v2, v2
	v_lshl_add_u64 v[6:7], v[18:19], 0, v[114:115]
	v_cvt_pk_bf16_f32 v3, v12, v13
	v_add_f32_e32 v2, 1.0, v2
	v_rcp_f32_e32 v2, v2
	s_nop 0
	v_mul_f32_e32 v2, v8, v2
	v_mul_f32_e32 v8, v2, v4
	v_mul_f32_e32 v2, 0xbfb8aa3b, v9
	v_exp_f32_e32 v2, v2
	v_cvt_pk_bf16_f32 v4, v14, v15
	s_nop 0
	v_add_f32_e32 v2, 1.0, v2
	v_rcp_f32_e32 v2, v2
	s_nop 0
	v_mul_f32_e32 v2, v9, v2
	v_mul_f32_e32 v5, v2, v5
	v_cvt_pk_bf16_f32 v2, v10, v11
	v_cvt_pk_bf16_f32 v5, v8, v5
	global_store_dwordx4 v[6:7], v[2:5], off
	s_cbranch_vccnz .Lgx_a_exit
	s_cmpk_gt_u32 s36, 0xff
	s_cbranch_scc0 .LBB0_874
	s_barrier
	s_branch .LBB0_874
.Lgx_a_exit:
	s_waitcnt vmcnt(0)
.LBB0_885:
	v_readlane_b32 s52, v253, 11
	v_readlane_b32 s53, v253, 12
	s_movk_i32 s48, 0x7000
	s_movk_i32 s45, 0x3fff
	s_mov_b32 s47, s94
	s_barrier
